# v25 + final RMS-norm loop rewritten: gain vector loaded once, rows double-buffered
# speedup vs baseline: 1.0088x; 1.0055x over previous
; __device__ __forceinline__ int otid() { int t = threadIdx.x; asm volatile("" : "+v"(t)); return t; }
; __device__ __forceinline__ void phase_final(const Args& a, int G) {
;     const int tid = otid(), lane = tid & 63, wave = tid >> 6;
;     const int gw = blockIdx.x * 8 + wave, NGW = G * 8;
;     const unsigned long long* rss = (const unsigned long long*)(a.ws + WS_RSS) + (size_t)6 * T; const float* gf = a.in[I_FINN];
;     for (int row = gw; row < T; row += NGW) {
;         const float rinv = rsqrtf((float)rss[row] * (1.f / (16777216.f * DM)) + EPS);
;         f32x4* xr = (f32x4*)(a.out + (size_t)row * DM) + lane; const f32x4* gr = (const f32x4*)gf + lane;
; #pragma unroll
;         for (int i = 0; i < 8; ++i) { f32x4 v = xr[64 * i]; const f32x4 gg = gr[64 * i]; v = v * rinv * gg; xr[64 * i] = v; }
;     }
; }
.LBB0_1073:
	global_load_dwordx4 v[64:67], v[0:1], off
	global_load_dwordx4 v[68:71], v[0:1], off offset:1024
	global_load_dwordx4 v[72:75], v[0:1], off offset:2048
	global_load_dwordx4 v[76:79], v[0:1], off offset:3072
	global_load_dwordx4 v[80:83], v[2:3], off
	global_load_dwordx4 v[84:87], v[2:3], off offset:1024
	global_load_dwordx4 v[88:91], v[2:3], off offset:2048
	global_load_dwordx4 v[92:95], v[2:3], off offset:3072
	global_load_dwordx2 v[30:31], v[10:11], off
	global_load_dwordx4 v[32:35], v[12:13], off offset:-4096
	global_load_dwordx4 v[36:39], v[12:13], off offset:-3072
	global_load_dwordx4 v[40:43], v[12:13], off offset:-2048
	global_load_dwordx4 v[44:47], v[12:13], off offset:-1024
	global_load_dwordx4 v[48:51], v[12:13], off offset:0
	global_load_dwordx4 v[52:55], v[12:13], off offset:1024
	global_load_dwordx4 v[56:59], v[12:13], off offset:2048
	global_load_dwordx4 v[60:63], v[12:13], off offset:3072
	v_mov_b64_e32 v[24:25], v[12:13]
	v_lshl_add_u64 v[10:11], v[10:11], 0, s[20:21]
	v_lshl_add_u64 v[12:13], v[12:13], 0, s[18:19]
	global_load_dwordx2 v[128:129], v[10:11], off
	global_load_dwordx4 v[96:99], v[12:13], off offset:-4096
	global_load_dwordx4 v[100:103], v[12:13], off offset:-3072
	global_load_dwordx4 v[104:107], v[12:13], off offset:-2048
	global_load_dwordx4 v[108:111], v[12:13], off offset:-1024
	global_load_dwordx4 v[112:115], v[12:13], off offset:0
	global_load_dwordx4 v[116:119], v[12:13], off offset:1024
	global_load_dwordx4 v[120:123], v[12:13], off offset:2048
	global_load_dwordx4 v[124:127], v[12:13], off offset:3072
	s_waitcnt vmcnt(9)
	v_ffbh_u32_e32 v20, v31
	v_min_u32_e32 v20, 32, v20
	v_lshlrev_b64 v[30:31], v20, v[30:31]
	v_min_u32_e32 v30, 1, v30
	v_or_b32_e32 v30, v31, v30
	v_cvt_f32_u32_e32 v30, v30
	v_sub_u32_e32 v20, 32, v20
	v_ldexp_f32 v20, v30, v20
	v_fmamk_f32 v20, v20, 0x2e000000, v176
	v_mul_f32_e32 v30, 0x4b800000, v20
	v_cmp_gt_f32_e32 vcc, s7, v20
	s_nop 1
	v_cndmask_b32_e32 v20, v20, v30, vcc
	v_rsq_f32_e32 v20, v20
	s_nop 0
	v_mul_f32_e32 v30, 0x45800000, v20
	v_cndmask_b32_e32 v22, v20, v30, vcc
	v_pk_mul_f32 v[32:33], v[32:33], v[22:23] op_sel_hi:[1,0]
	v_pk_mul_f32 v[34:35], v[34:35], v[22:23] op_sel_hi:[1,0]
	v_pk_mul_f32 v[36:37], v[36:37], v[22:23] op_sel_hi:[1,0]
	v_pk_mul_f32 v[38:39], v[38:39], v[22:23] op_sel_hi:[1,0]
	v_pk_mul_f32 v[40:41], v[40:41], v[22:23] op_sel_hi:[1,0]
	v_pk_mul_f32 v[42:43], v[42:43], v[22:23] op_sel_hi:[1,0]
	v_pk_mul_f32 v[44:45], v[44:45], v[22:23] op_sel_hi:[1,0]
	v_pk_mul_f32 v[46:47], v[46:47], v[22:23] op_sel_hi:[1,0]
	v_pk_mul_f32 v[48:49], v[48:49], v[22:23] op_sel_hi:[1,0]
	v_pk_mul_f32 v[50:51], v[50:51], v[22:23] op_sel_hi:[1,0]
	v_pk_mul_f32 v[52:53], v[52:53], v[22:23] op_sel_hi:[1,0]
	v_pk_mul_f32 v[54:55], v[54:55], v[22:23] op_sel_hi:[1,0]
	v_pk_mul_f32 v[56:57], v[56:57], v[22:23] op_sel_hi:[1,0]
	v_pk_mul_f32 v[58:59], v[58:59], v[22:23] op_sel_hi:[1,0]
	v_pk_mul_f32 v[60:61], v[60:61], v[22:23] op_sel_hi:[1,0]
	v_pk_mul_f32 v[62:63], v[62:63], v[22:23] op_sel_hi:[1,0]
	v_pk_mul_f32 v[32:33], v[64:65], v[32:33]
	v_pk_mul_f32 v[34:35], v[66:67], v[34:35]
	v_pk_mul_f32 v[36:37], v[68:69], v[36:37]
	v_pk_mul_f32 v[38:39], v[70:71], v[38:39]
	v_pk_mul_f32 v[40:41], v[72:73], v[40:41]
	v_pk_mul_f32 v[42:43], v[74:75], v[42:43]
	v_pk_mul_f32 v[44:45], v[76:77], v[44:45]
	v_pk_mul_f32 v[46:47], v[78:79], v[46:47]
	v_pk_mul_f32 v[48:49], v[80:81], v[48:49]
	v_pk_mul_f32 v[50:51], v[82:83], v[50:51]
	v_pk_mul_f32 v[52:53], v[84:85], v[52:53]
	v_pk_mul_f32 v[54:55], v[86:87], v[54:55]
	v_pk_mul_f32 v[56:57], v[88:89], v[56:57]
	v_pk_mul_f32 v[58:59], v[90:91], v[58:59]
	v_pk_mul_f32 v[60:61], v[92:93], v[60:61]
	v_pk_mul_f32 v[62:63], v[94:95], v[62:63]
	global_store_dwordx4 v[24:25], v[32:35], off offset:-4096
	global_store_dwordx4 v[24:25], v[36:39], off offset:-3072
	global_store_dwordx4 v[24:25], v[40:43], off offset:-2048
	global_store_dwordx4 v[24:25], v[44:47], off offset:-1024
	global_store_dwordx4 v[24:25], v[48:51], off offset:0
	global_store_dwordx4 v[24:25], v[52:55], off offset:1024
	global_store_dwordx4 v[24:25], v[56:59], off offset:2048
	global_store_dwordx4 v[24:25], v[60:63], off offset:3072
	v_mov_b64_e32 v[24:25], v[12:13]
	v_lshl_add_u64 v[10:11], v[10:11], 0, s[20:21]
	v_lshl_add_u64 v[12:13], v[12:13], 0, s[18:19]
	global_load_dwordx2 v[30:31], v[10:11], off
	global_load_dwordx4 v[32:35], v[12:13], off offset:-4096
	global_load_dwordx4 v[36:39], v[12:13], off offset:-3072
	global_load_dwordx4 v[40:43], v[12:13], off offset:-2048
	global_load_dwordx4 v[44:47], v[12:13], off offset:-1024
	global_load_dwordx4 v[48:51], v[12:13], off offset:0
	global_load_dwordx4 v[52:55], v[12:13], off offset:1024
	global_load_dwordx4 v[56:59], v[12:13], off offset:2048
	global_load_dwordx4 v[60:63], v[12:13], off offset:3072
	s_waitcnt vmcnt(17)
; __device__ __forceinline__ int otid() { int t = threadIdx.x; asm volatile("" : "+v"(t)); return t; }
; __device__ __forceinline__ void phase_final(const Args& a, int G) {
;     const int tid = otid(), lane = tid & 63, wave = tid >> 6;
;     const int gw = blockIdx.x * 8 + wave, NGW = G * 8;
;     const unsigned long long* rss = (const unsigned long long*)(a.ws + WS_RSS) + (size_t)6 * T; const float* gf = a.in[I_FINN];
;     for (int row = gw; row < T; row += NGW) {
;         const float rinv = rsqrtf((float)rss[row] * (1.f / (16777216.f * DM)) + EPS);
;         f32x4* xr = (f32x4*)(a.out + (size_t)row * DM) + lane; const f32x4* gr = (const f32x4*)gf + lane;
; #pragma unroll
;         for (int i = 0; i < 8; ++i) { f32x4 v = xr[64 * i]; const f32x4 gg = gr[64 * i]; v = v * rinv * gg; xr[64 * i] = v; }
;     }
; }
	v_ffbh_u32_e32 v20, v129
	v_min_u32_e32 v20, 32, v20
	v_lshlrev_b64 v[128:129], v20, v[128:129]
	v_min_u32_e32 v128, 1, v128
	v_or_b32_e32 v128, v129, v128
	v_cvt_f32_u32_e32 v128, v128
	v_sub_u32_e32 v20, 32, v20
	v_ldexp_f32 v20, v128, v20
	v_fmamk_f32 v20, v20, 0x2e000000, v176
	v_mul_f32_e32 v128, 0x4b800000, v20
	v_cmp_gt_f32_e32 vcc, s7, v20
	s_nop 1
	v_cndmask_b32_e32 v20, v20, v128, vcc
	v_rsq_f32_e32 v20, v20
	s_nop 0
	v_mul_f32_e32 v128, 0x45800000, v20
	v_cndmask_b32_e32 v22, v20, v128, vcc
	v_pk_mul_f32 v[96:97], v[96:97], v[22:23] op_sel_hi:[1,0]
	v_pk_mul_f32 v[98:99], v[98:99], v[22:23] op_sel_hi:[1,0]
	v_pk_mul_f32 v[100:101], v[100:101], v[22:23] op_sel_hi:[1,0]
	v_pk_mul_f32 v[102:103], v[102:103], v[22:23] op_sel_hi:[1,0]
	v_pk_mul_f32 v[104:105], v[104:105], v[22:23] op_sel_hi:[1,0]
	v_pk_mul_f32 v[106:107], v[106:107], v[22:23] op_sel_hi:[1,0]
	v_pk_mul_f32 v[108:109], v[108:109], v[22:23] op_sel_hi:[1,0]
	v_pk_mul_f32 v[110:111], v[110:111], v[22:23] op_sel_hi:[1,0]
	v_pk_mul_f32 v[112:113], v[112:113], v[22:23] op_sel_hi:[1,0]
	v_pk_mul_f32 v[114:115], v[114:115], v[22:23] op_sel_hi:[1,0]
	v_pk_mul_f32 v[116:117], v[116:117], v[22:23] op_sel_hi:[1,0]
	v_pk_mul_f32 v[118:119], v[118:119], v[22:23] op_sel_hi:[1,0]
	v_pk_mul_f32 v[120:121], v[120:121], v[22:23] op_sel_hi:[1,0]
	v_pk_mul_f32 v[122:123], v[122:123], v[22:23] op_sel_hi:[1,0]
	v_pk_mul_f32 v[124:125], v[124:125], v[22:23] op_sel_hi:[1,0]
	v_pk_mul_f32 v[126:127], v[126:127], v[22:23] op_sel_hi:[1,0]
	v_pk_mul_f32 v[96:97], v[64:65], v[96:97]
	v_pk_mul_f32 v[98:99], v[66:67], v[98:99]
	v_pk_mul_f32 v[100:101], v[68:69], v[100:101]
	v_pk_mul_f32 v[102:103], v[70:71], v[102:103]
	v_pk_mul_f32 v[104:105], v[72:73], v[104:105]
	v_pk_mul_f32 v[106:107], v[74:75], v[106:107]
	v_pk_mul_f32 v[108:109], v[76:77], v[108:109]
	v_pk_mul_f32 v[110:111], v[78:79], v[110:111]
	v_pk_mul_f32 v[112:113], v[80:81], v[112:113]
	v_pk_mul_f32 v[114:115], v[82:83], v[114:115]
	v_pk_mul_f32 v[116:117], v[84:85], v[116:117]
	v_pk_mul_f32 v[118:119], v[86:87], v[118:119]
	v_pk_mul_f32 v[120:121], v[88:89], v[120:121]
	v_pk_mul_f32 v[122:123], v[90:91], v[122:123]
	v_pk_mul_f32 v[124:125], v[92:93], v[124:125]
	v_pk_mul_f32 v[126:127], v[94:95], v[126:127]
	global_store_dwordx4 v[24:25], v[96:99], off offset:-4096
	global_store_dwordx4 v[24:25], v[100:103], off offset:-3072
	global_store_dwordx4 v[24:25], v[104:107], off offset:-2048
	global_store_dwordx4 v[24:25], v[108:111], off offset:-1024
	global_store_dwordx4 v[24:25], v[112:115], off offset:0
	global_store_dwordx4 v[24:25], v[116:119], off offset:1024
	global_store_dwordx4 v[24:25], v[120:123], off offset:2048
	global_store_dwordx4 v[24:25], v[124:127], off offset:3072
	v_mov_b64_e32 v[24:25], v[12:13]
	v_lshl_add_u64 v[10:11], v[10:11], 0, s[20:21]
	v_lshl_add_u64 v[12:13], v[12:13], 0, s[18:19]
	global_load_dwordx2 v[128:129], v[10:11], off
	global_load_dwordx4 v[96:99], v[12:13], off offset:-4096
	global_load_dwordx4 v[100:103], v[12:13], off offset:-3072
	global_load_dwordx4 v[104:107], v[12:13], off offset:-2048
	global_load_dwordx4 v[108:111], v[12:13], off offset:-1024
	global_load_dwordx4 v[112:115], v[12:13], off offset:0
	global_load_dwordx4 v[116:119], v[12:13], off offset:1024
	global_load_dwordx4 v[120:123], v[12:13], off offset:2048
	global_load_dwordx4 v[124:127], v[12:13], off offset:3072
	s_waitcnt vmcnt(17)
	v_ffbh_u32_e32 v20, v31
	v_min_u32_e32 v20, 32, v20
	v_lshlrev_b64 v[30:31], v20, v[30:31]
	v_min_u32_e32 v30, 1, v30
	v_or_b32_e32 v30, v31, v30
	v_cvt_f32_u32_e32 v30, v30
	v_sub_u32_e32 v20, 32, v20
	v_ldexp_f32 v20, v30, v20
	v_fmamk_f32 v20, v20, 0x2e000000, v176
	v_mul_f32_e32 v30, 0x4b800000, v20
	v_cmp_gt_f32_e32 vcc, s7, v20
	s_nop 1
	v_cndmask_b32_e32 v20, v20, v30, vcc
	v_rsq_f32_e32 v20, v20
	s_nop 0
	v_mul_f32_e32 v30, 0x45800000, v20
	v_cndmask_b32_e32 v22, v20, v30, vcc
	v_pk_mul_f32 v[32:33], v[32:33], v[22:23] op_sel_hi:[1,0]
	v_pk_mul_f32 v[34:35], v[34:35], v[22:23] op_sel_hi:[1,0]
	v_pk_mul_f32 v[36:37], v[36:37], v[22:23] op_sel_hi:[1,0]
	v_pk_mul_f32 v[38:39], v[38:39], v[22:23] op_sel_hi:[1,0]
	v_pk_mul_f32 v[40:41], v[40:41], v[22:23] op_sel_hi:[1,0]
	v_pk_mul_f32 v[42:43], v[42:43], v[22:23] op_sel_hi:[1,0]
	v_pk_mul_f32 v[44:45], v[44:45], v[22:23] op_sel_hi:[1,0]
	v_pk_mul_f32 v[46:47], v[46:47], v[22:23] op_sel_hi:[1,0]
	v_pk_mul_f32 v[48:49], v[48:49], v[22:23] op_sel_hi:[1,0]
	v_pk_mul_f32 v[50:51], v[50:51], v[22:23] op_sel_hi:[1,0]
	v_pk_mul_f32 v[52:53], v[52:53], v[22:23] op_sel_hi:[1,0]
	v_pk_mul_f32 v[54:55], v[54:55], v[22:23] op_sel_hi:[1,0]
	v_pk_mul_f32 v[56:57], v[56:57], v[22:23] op_sel_hi:[1,0]
	v_pk_mul_f32 v[58:59], v[58:59], v[22:23] op_sel_hi:[1,0]
	v_pk_mul_f32 v[60:61], v[60:61], v[22:23] op_sel_hi:[1,0]
	v_pk_mul_f32 v[62:63], v[62:63], v[22:23] op_sel_hi:[1,0]
	v_pk_mul_f32 v[32:33], v[64:65], v[32:33]
	v_pk_mul_f32 v[34:35], v[66:67], v[34:35]
	v_pk_mul_f32 v[36:37], v[68:69], v[36:37]
	v_pk_mul_f32 v[38:39], v[70:71], v[38:39]
	v_pk_mul_f32 v[40:41], v[72:73], v[40:41]
	v_pk_mul_f32 v[42:43], v[74:75], v[42:43]
	v_pk_mul_f32 v[44:45], v[76:77], v[44:45]
	v_pk_mul_f32 v[46:47], v[78:79], v[46:47]
	v_pk_mul_f32 v[48:49], v[80:81], v[48:49]
	v_pk_mul_f32 v[50:51], v[82:83], v[50:51]
	v_pk_mul_f32 v[52:53], v[84:85], v[52:53]
	v_pk_mul_f32 v[54:55], v[86:87], v[54:55]
	v_pk_mul_f32 v[56:57], v[88:89], v[56:57]
	v_pk_mul_f32 v[58:59], v[90:91], v[58:59]
	v_pk_mul_f32 v[60:61], v[92:93], v[60:61]
	v_pk_mul_f32 v[62:63], v[94:95], v[62:63]
	global_store_dwordx4 v[24:25], v[32:35], off offset:-4096
	global_store_dwordx4 v[24:25], v[36:39], off offset:-3072
	global_store_dwordx4 v[24:25], v[40:43], off offset:-2048
	global_store_dwordx4 v[24:25], v[44:47], off offset:-1024
	global_store_dwordx4 v[24:25], v[48:51], off offset:0
	global_store_dwordx4 v[24:25], v[52:55], off offset:1024
	global_store_dwordx4 v[24:25], v[56:59], off offset:2048
	global_store_dwordx4 v[24:25], v[60:63], off offset:3072
	v_mov_b64_e32 v[24:25], v[12:13]
	v_lshl_add_u64 v[10:11], v[10:11], 0, s[20:21]
	v_lshl_add_u64 v[12:13], v[12:13], 0, s[18:19]
	global_load_dwordx2 v[30:31], v[10:11], off
	global_load_dwordx4 v[32:35], v[12:13], off offset:-4096
	global_load_dwordx4 v[36:39], v[12:13], off offset:-3072
	global_load_dwordx4 v[40:43], v[12:13], off offset:-2048
	global_load_dwordx4 v[44:47], v[12:13], off offset:-1024
	global_load_dwordx4 v[48:51], v[12:13], off offset:0
	global_load_dwordx4 v[52:55], v[12:13], off offset:1024
	global_load_dwordx4 v[56:59], v[12:13], off offset:2048
	global_load_dwordx4 v[60:63], v[12:13], off offset:3072
	s_waitcnt vmcnt(17)
; __device__ __forceinline__ int otid() { int t = threadIdx.x; asm volatile("" : "+v"(t)); return t; }
; __device__ __forceinline__ void phase_final(const Args& a, int G) {
;     const int tid = otid(), lane = tid & 63, wave = tid >> 6;
;     const int gw = blockIdx.x * 8 + wave, NGW = G * 8;
;     const unsigned long long* rss = (const unsigned long long*)(a.ws + WS_RSS) + (size_t)6 * T; const float* gf = a.in[I_FINN];
;     for (int row = gw; row < T; row += NGW) {
;         const float rinv = rsqrtf((float)rss[row] * (1.f / (16777216.f * DM)) + EPS);
;         f32x4* xr = (f32x4*)(a.out + (size_t)row * DM) + lane; const f32x4* gr = (const f32x4*)gf + lane;
; #pragma unroll
;         for (int i = 0; i < 8; ++i) { f32x4 v = xr[64 * i]; const f32x4 gg = gr[64 * i]; v = v * rinv * gg; xr[64 * i] = v; }
;     }
; }
	v_ffbh_u32_e32 v20, v129
	v_min_u32_e32 v20, 32, v20
	v_lshlrev_b64 v[128:129], v20, v[128:129]
	v_min_u32_e32 v128, 1, v128
	v_or_b32_e32 v128, v129, v128
	v_cvt_f32_u32_e32 v128, v128
	v_sub_u32_e32 v20, 32, v20
	v_ldexp_f32 v20, v128, v20
	v_fmamk_f32 v20, v20, 0x2e000000, v176
	v_mul_f32_e32 v128, 0x4b800000, v20
	v_cmp_gt_f32_e32 vcc, s7, v20
	s_nop 1
	v_cndmask_b32_e32 v20, v20, v128, vcc
	v_rsq_f32_e32 v20, v20
	s_nop 0
	v_mul_f32_e32 v128, 0x45800000, v20
	v_cndmask_b32_e32 v22, v20, v128, vcc
	v_pk_mul_f32 v[96:97], v[96:97], v[22:23] op_sel_hi:[1,0]
	v_pk_mul_f32 v[98:99], v[98:99], v[22:23] op_sel_hi:[1,0]
	v_pk_mul_f32 v[100:101], v[100:101], v[22:23] op_sel_hi:[1,0]
	v_pk_mul_f32 v[102:103], v[102:103], v[22:23] op_sel_hi:[1,0]
	v_pk_mul_f32 v[104:105], v[104:105], v[22:23] op_sel_hi:[1,0]
	v_pk_mul_f32 v[106:107], v[106:107], v[22:23] op_sel_hi:[1,0]
	v_pk_mul_f32 v[108:109], v[108:109], v[22:23] op_sel_hi:[1,0]
	v_pk_mul_f32 v[110:111], v[110:111], v[22:23] op_sel_hi:[1,0]
	v_pk_mul_f32 v[112:113], v[112:113], v[22:23] op_sel_hi:[1,0]
	v_pk_mul_f32 v[114:115], v[114:115], v[22:23] op_sel_hi:[1,0]
	v_pk_mul_f32 v[116:117], v[116:117], v[22:23] op_sel_hi:[1,0]
	v_pk_mul_f32 v[118:119], v[118:119], v[22:23] op_sel_hi:[1,0]
	v_pk_mul_f32 v[120:121], v[120:121], v[22:23] op_sel_hi:[1,0]
	v_pk_mul_f32 v[122:123], v[122:123], v[22:23] op_sel_hi:[1,0]
	v_pk_mul_f32 v[124:125], v[124:125], v[22:23] op_sel_hi:[1,0]
	v_pk_mul_f32 v[126:127], v[126:127], v[22:23] op_sel_hi:[1,0]
	v_pk_mul_f32 v[96:97], v[64:65], v[96:97]
	v_pk_mul_f32 v[98:99], v[66:67], v[98:99]
	v_pk_mul_f32 v[100:101], v[68:69], v[100:101]
	v_pk_mul_f32 v[102:103], v[70:71], v[102:103]
	v_pk_mul_f32 v[104:105], v[72:73], v[104:105]
	v_pk_mul_f32 v[106:107], v[74:75], v[106:107]
	v_pk_mul_f32 v[108:109], v[76:77], v[108:109]
	v_pk_mul_f32 v[110:111], v[78:79], v[110:111]
	v_pk_mul_f32 v[112:113], v[80:81], v[112:113]
	v_pk_mul_f32 v[114:115], v[82:83], v[114:115]
	v_pk_mul_f32 v[116:117], v[84:85], v[116:117]
	v_pk_mul_f32 v[118:119], v[86:87], v[118:119]
	v_pk_mul_f32 v[120:121], v[88:89], v[120:121]
	v_pk_mul_f32 v[122:123], v[90:91], v[122:123]
	v_pk_mul_f32 v[124:125], v[92:93], v[124:125]
	v_pk_mul_f32 v[126:127], v[94:95], v[126:127]
	global_store_dwordx4 v[24:25], v[96:99], off offset:-4096
	global_store_dwordx4 v[24:25], v[100:103], off offset:-3072
	global_store_dwordx4 v[24:25], v[104:107], off offset:-2048
	global_store_dwordx4 v[24:25], v[108:111], off offset:-1024
	global_store_dwordx4 v[24:25], v[112:115], off offset:0
	global_store_dwordx4 v[24:25], v[116:119], off offset:1024
	global_store_dwordx4 v[24:25], v[120:123], off offset:2048
	global_store_dwordx4 v[24:25], v[124:127], off offset:3072
	v_mov_b64_e32 v[24:25], v[12:13]
	v_lshl_add_u64 v[10:11], v[10:11], 0, s[20:21]
	v_lshl_add_u64 v[12:13], v[12:13], 0, s[18:19]
	global_load_dwordx2 v[128:129], v[10:11], off
	global_load_dwordx4 v[96:99], v[12:13], off offset:-4096
	global_load_dwordx4 v[100:103], v[12:13], off offset:-3072
	global_load_dwordx4 v[104:107], v[12:13], off offset:-2048
	global_load_dwordx4 v[108:111], v[12:13], off offset:-1024
	global_load_dwordx4 v[112:115], v[12:13], off offset:0
	global_load_dwordx4 v[116:119], v[12:13], off offset:1024
	global_load_dwordx4 v[120:123], v[12:13], off offset:2048
	global_load_dwordx4 v[124:127], v[12:13], off offset:3072
	s_waitcnt vmcnt(17)
	v_ffbh_u32_e32 v20, v31
	v_min_u32_e32 v20, 32, v20
	v_lshlrev_b64 v[30:31], v20, v[30:31]
	v_min_u32_e32 v30, 1, v30
	v_or_b32_e32 v30, v31, v30
	v_cvt_f32_u32_e32 v30, v30
	v_sub_u32_e32 v20, 32, v20
	v_ldexp_f32 v20, v30, v20
	v_fmamk_f32 v20, v20, 0x2e000000, v176
	v_mul_f32_e32 v30, 0x4b800000, v20
	v_cmp_gt_f32_e32 vcc, s7, v20
	s_nop 1
	v_cndmask_b32_e32 v20, v20, v30, vcc
	v_rsq_f32_e32 v20, v20
	s_nop 0
	v_mul_f32_e32 v30, 0x45800000, v20
	v_cndmask_b32_e32 v22, v20, v30, vcc
	v_pk_mul_f32 v[32:33], v[32:33], v[22:23] op_sel_hi:[1,0]
	v_pk_mul_f32 v[34:35], v[34:35], v[22:23] op_sel_hi:[1,0]
	v_pk_mul_f32 v[36:37], v[36:37], v[22:23] op_sel_hi:[1,0]
	v_pk_mul_f32 v[38:39], v[38:39], v[22:23] op_sel_hi:[1,0]
	v_pk_mul_f32 v[40:41], v[40:41], v[22:23] op_sel_hi:[1,0]
	v_pk_mul_f32 v[42:43], v[42:43], v[22:23] op_sel_hi:[1,0]
	v_pk_mul_f32 v[44:45], v[44:45], v[22:23] op_sel_hi:[1,0]
	v_pk_mul_f32 v[46:47], v[46:47], v[22:23] op_sel_hi:[1,0]
	v_pk_mul_f32 v[48:49], v[48:49], v[22:23] op_sel_hi:[1,0]
	v_pk_mul_f32 v[50:51], v[50:51], v[22:23] op_sel_hi:[1,0]
	v_pk_mul_f32 v[52:53], v[52:53], v[22:23] op_sel_hi:[1,0]
	v_pk_mul_f32 v[54:55], v[54:55], v[22:23] op_sel_hi:[1,0]
	v_pk_mul_f32 v[56:57], v[56:57], v[22:23] op_sel_hi:[1,0]
	v_pk_mul_f32 v[58:59], v[58:59], v[22:23] op_sel_hi:[1,0]
	v_pk_mul_f32 v[60:61], v[60:61], v[22:23] op_sel_hi:[1,0]
	v_pk_mul_f32 v[62:63], v[62:63], v[22:23] op_sel_hi:[1,0]
	v_pk_mul_f32 v[32:33], v[64:65], v[32:33]
	v_pk_mul_f32 v[34:35], v[66:67], v[34:35]
	v_pk_mul_f32 v[36:37], v[68:69], v[36:37]
	v_pk_mul_f32 v[38:39], v[70:71], v[38:39]
	v_pk_mul_f32 v[40:41], v[72:73], v[40:41]
	v_pk_mul_f32 v[42:43], v[74:75], v[42:43]
	v_pk_mul_f32 v[44:45], v[76:77], v[44:45]
	v_pk_mul_f32 v[46:47], v[78:79], v[46:47]
	v_pk_mul_f32 v[48:49], v[80:81], v[48:49]
	v_pk_mul_f32 v[50:51], v[82:83], v[50:51]
	v_pk_mul_f32 v[52:53], v[84:85], v[52:53]
	v_pk_mul_f32 v[54:55], v[86:87], v[54:55]
	v_pk_mul_f32 v[56:57], v[88:89], v[56:57]
	v_pk_mul_f32 v[58:59], v[90:91], v[58:59]
	v_pk_mul_f32 v[60:61], v[92:93], v[60:61]
	v_pk_mul_f32 v[62:63], v[94:95], v[62:63]
	global_store_dwordx4 v[24:25], v[32:35], off offset:-4096
	global_store_dwordx4 v[24:25], v[36:39], off offset:-3072
	global_store_dwordx4 v[24:25], v[40:43], off offset:-2048
	global_store_dwordx4 v[24:25], v[44:47], off offset:-1024
	global_store_dwordx4 v[24:25], v[48:51], off offset:0
	global_store_dwordx4 v[24:25], v[52:55], off offset:1024
	global_store_dwordx4 v[24:25], v[56:59], off offset:2048
	global_store_dwordx4 v[24:25], v[60:63], off offset:3072
	v_mov_b64_e32 v[24:25], v[12:13]
	v_lshl_add_u64 v[10:11], v[10:11], 0, s[20:21]
	v_lshl_add_u64 v[12:13], v[12:13], 0, s[18:19]
	global_load_dwordx2 v[30:31], v[10:11], off
	global_load_dwordx4 v[32:35], v[12:13], off offset:-4096
	global_load_dwordx4 v[36:39], v[12:13], off offset:-3072
	global_load_dwordx4 v[40:43], v[12:13], off offset:-2048
	global_load_dwordx4 v[44:47], v[12:13], off offset:-1024
	global_load_dwordx4 v[48:51], v[12:13], off offset:0
	global_load_dwordx4 v[52:55], v[12:13], off offset:1024
	global_load_dwordx4 v[56:59], v[12:13], off offset:2048
	global_load_dwordx4 v[60:63], v[12:13], off offset:3072
	s_waitcnt vmcnt(17)
; __device__ __forceinline__ int otid() { int t = threadIdx.x; asm volatile("" : "+v"(t)); return t; }
; __device__ __forceinline__ void phase_final(const Args& a, int G) {
;     const int tid = otid(), lane = tid & 63, wave = tid >> 6;
;     const int gw = blockIdx.x * 8 + wave, NGW = G * 8;
;     const unsigned long long* rss = (const unsigned long long*)(a.ws + WS_RSS) + (size_t)6 * T; const float* gf = a.in[I_FINN];
;     for (int row = gw; row < T; row += NGW) {
;         const float rinv = rsqrtf((float)rss[row] * (1.f / (16777216.f * DM)) + EPS);
;         f32x4* xr = (f32x4*)(a.out + (size_t)row * DM) + lane; const f32x4* gr = (const f32x4*)gf + lane;
; #pragma unroll
;         for (int i = 0; i < 8; ++i) { f32x4 v = xr[64 * i]; const f32x4 gg = gr[64 * i]; v = v * rinv * gg; xr[64 * i] = v; }
;     }
; }
	v_ffbh_u32_e32 v20, v129
	v_min_u32_e32 v20, 32, v20
	v_lshlrev_b64 v[128:129], v20, v[128:129]
	v_min_u32_e32 v128, 1, v128
	v_or_b32_e32 v128, v129, v128
	v_cvt_f32_u32_e32 v128, v128
	v_sub_u32_e32 v20, 32, v20
	v_ldexp_f32 v20, v128, v20
	v_fmamk_f32 v20, v20, 0x2e000000, v176
	v_mul_f32_e32 v128, 0x4b800000, v20
	v_cmp_gt_f32_e32 vcc, s7, v20
	s_nop 1
	v_cndmask_b32_e32 v20, v20, v128, vcc
	v_rsq_f32_e32 v20, v20
	s_nop 0
	v_mul_f32_e32 v128, 0x45800000, v20
	v_cndmask_b32_e32 v22, v20, v128, vcc
	v_pk_mul_f32 v[96:97], v[96:97], v[22:23] op_sel_hi:[1,0]
	v_pk_mul_f32 v[98:99], v[98:99], v[22:23] op_sel_hi:[1,0]
	v_pk_mul_f32 v[100:101], v[100:101], v[22:23] op_sel_hi:[1,0]
	v_pk_mul_f32 v[102:103], v[102:103], v[22:23] op_sel_hi:[1,0]
	v_pk_mul_f32 v[104:105], v[104:105], v[22:23] op_sel_hi:[1,0]
	v_pk_mul_f32 v[106:107], v[106:107], v[22:23] op_sel_hi:[1,0]
	v_pk_mul_f32 v[108:109], v[108:109], v[22:23] op_sel_hi:[1,0]
	v_pk_mul_f32 v[110:111], v[110:111], v[22:23] op_sel_hi:[1,0]
	v_pk_mul_f32 v[112:113], v[112:113], v[22:23] op_sel_hi:[1,0]
	v_pk_mul_f32 v[114:115], v[114:115], v[22:23] op_sel_hi:[1,0]
	v_pk_mul_f32 v[116:117], v[116:117], v[22:23] op_sel_hi:[1,0]
	v_pk_mul_f32 v[118:119], v[118:119], v[22:23] op_sel_hi:[1,0]
	v_pk_mul_f32 v[120:121], v[120:121], v[22:23] op_sel_hi:[1,0]
	v_pk_mul_f32 v[122:123], v[122:123], v[22:23] op_sel_hi:[1,0]
	v_pk_mul_f32 v[124:125], v[124:125], v[22:23] op_sel_hi:[1,0]
	v_pk_mul_f32 v[126:127], v[126:127], v[22:23] op_sel_hi:[1,0]
	v_pk_mul_f32 v[96:97], v[64:65], v[96:97]
	v_pk_mul_f32 v[98:99], v[66:67], v[98:99]
	v_pk_mul_f32 v[100:101], v[68:69], v[100:101]
	v_pk_mul_f32 v[102:103], v[70:71], v[102:103]
	v_pk_mul_f32 v[104:105], v[72:73], v[104:105]
	v_pk_mul_f32 v[106:107], v[74:75], v[106:107]
	v_pk_mul_f32 v[108:109], v[76:77], v[108:109]
	v_pk_mul_f32 v[110:111], v[78:79], v[110:111]
	v_pk_mul_f32 v[112:113], v[80:81], v[112:113]
	v_pk_mul_f32 v[114:115], v[82:83], v[114:115]
	v_pk_mul_f32 v[116:117], v[84:85], v[116:117]
	v_pk_mul_f32 v[118:119], v[86:87], v[118:119]
	v_pk_mul_f32 v[120:121], v[88:89], v[120:121]
	v_pk_mul_f32 v[122:123], v[90:91], v[122:123]
	v_pk_mul_f32 v[124:125], v[92:93], v[124:125]
	v_pk_mul_f32 v[126:127], v[94:95], v[126:127]
	global_store_dwordx4 v[24:25], v[96:99], off offset:-4096
	global_store_dwordx4 v[24:25], v[100:103], off offset:-3072
	global_store_dwordx4 v[24:25], v[104:107], off offset:-2048
	global_store_dwordx4 v[24:25], v[108:111], off offset:-1024
	global_store_dwordx4 v[24:25], v[112:115], off offset:0
	global_store_dwordx4 v[24:25], v[116:119], off offset:1024
	global_store_dwordx4 v[24:25], v[120:123], off offset:2048
	global_store_dwordx4 v[24:25], v[124:127], off offset:3072
	v_mov_b64_e32 v[24:25], v[12:13]
	v_lshl_add_u64 v[10:11], v[10:11], 0, s[20:21]
	v_lshl_add_u64 v[12:13], v[12:13], 0, s[18:19]
	global_load_dwordx2 v[128:129], v[10:11], off
	global_load_dwordx4 v[96:99], v[12:13], off offset:-4096
	global_load_dwordx4 v[100:103], v[12:13], off offset:-3072
	global_load_dwordx4 v[104:107], v[12:13], off offset:-2048
	global_load_dwordx4 v[108:111], v[12:13], off offset:-1024
	global_load_dwordx4 v[112:115], v[12:13], off offset:0
	global_load_dwordx4 v[116:119], v[12:13], off offset:1024
	global_load_dwordx4 v[120:123], v[12:13], off offset:2048
	global_load_dwordx4 v[124:127], v[12:13], off offset:3072
	s_waitcnt vmcnt(17)
; __device__ __forceinline__ int otid() { int t = threadIdx.x; asm volatile("" : "+v"(t)); return t; }
; __device__ __forceinline__ void phase_final(const Args& a, int G) {
;     const int tid = otid(), lane = tid & 63, wave = tid >> 6;
;     const int gw = blockIdx.x * 8 + wave, NGW = G * 8;
;     const unsigned long long* rss = (const unsigned long long*)(a.ws + WS_RSS) + (size_t)6 * T; const float* gf = a.in[I_FINN];
;     for (int row = gw; row < T; row += NGW) {
;         const float rinv = rsqrtf((float)rss[row] * (1.f / (16777216.f * DM)) + EPS);
;         f32x4* xr = (f32x4*)(a.out + (size_t)row * DM) + lane; const f32x4* gr = (const f32x4*)gf + lane;
; #pragma unroll
;         for (int i = 0; i < 8; ++i) { f32x4 v = xr[64 * i]; const f32x4 gg = gr[64 * i]; v = v * rinv * gg; xr[64 * i] = v; }
;     }
; }
	v_ffbh_u32_e32 v20, v31
	v_min_u32_e32 v20, 32, v20
	v_lshlrev_b64 v[30:31], v20, v[30:31]
	v_min_u32_e32 v30, 1, v30
	v_or_b32_e32 v30, v31, v30
	v_cvt_f32_u32_e32 v30, v30
	v_sub_u32_e32 v20, 32, v20
	v_ldexp_f32 v20, v30, v20
	v_fmamk_f32 v20, v20, 0x2e000000, v176
	v_mul_f32_e32 v30, 0x4b800000, v20
	v_cmp_gt_f32_e32 vcc, s7, v20
	s_nop 1
	v_cndmask_b32_e32 v20, v20, v30, vcc
	v_rsq_f32_e32 v20, v20
	s_nop 0
	v_mul_f32_e32 v30, 0x45800000, v20
	v_cndmask_b32_e32 v22, v20, v30, vcc
	v_pk_mul_f32 v[32:33], v[32:33], v[22:23] op_sel_hi:[1,0]
	v_pk_mul_f32 v[34:35], v[34:35], v[22:23] op_sel_hi:[1,0]
	v_pk_mul_f32 v[36:37], v[36:37], v[22:23] op_sel_hi:[1,0]
	v_pk_mul_f32 v[38:39], v[38:39], v[22:23] op_sel_hi:[1,0]
	v_pk_mul_f32 v[40:41], v[40:41], v[22:23] op_sel_hi:[1,0]
	v_pk_mul_f32 v[42:43], v[42:43], v[22:23] op_sel_hi:[1,0]
	v_pk_mul_f32 v[44:45], v[44:45], v[22:23] op_sel_hi:[1,0]
	v_pk_mul_f32 v[46:47], v[46:47], v[22:23] op_sel_hi:[1,0]
	v_pk_mul_f32 v[48:49], v[48:49], v[22:23] op_sel_hi:[1,0]
	v_pk_mul_f32 v[50:51], v[50:51], v[22:23] op_sel_hi:[1,0]
	v_pk_mul_f32 v[52:53], v[52:53], v[22:23] op_sel_hi:[1,0]
	v_pk_mul_f32 v[54:55], v[54:55], v[22:23] op_sel_hi:[1,0]
	v_pk_mul_f32 v[56:57], v[56:57], v[22:23] op_sel_hi:[1,0]
	v_pk_mul_f32 v[58:59], v[58:59], v[22:23] op_sel_hi:[1,0]
	v_pk_mul_f32 v[60:61], v[60:61], v[22:23] op_sel_hi:[1,0]
	v_pk_mul_f32 v[62:63], v[62:63], v[22:23] op_sel_hi:[1,0]
	v_pk_mul_f32 v[32:33], v[64:65], v[32:33]
	v_pk_mul_f32 v[34:35], v[66:67], v[34:35]
	v_pk_mul_f32 v[36:37], v[68:69], v[36:37]
	v_pk_mul_f32 v[38:39], v[70:71], v[38:39]
	v_pk_mul_f32 v[40:41], v[72:73], v[40:41]
	v_pk_mul_f32 v[42:43], v[74:75], v[42:43]
	v_pk_mul_f32 v[44:45], v[76:77], v[44:45]
	v_pk_mul_f32 v[46:47], v[78:79], v[46:47]
	v_pk_mul_f32 v[48:49], v[80:81], v[48:49]
	v_pk_mul_f32 v[50:51], v[82:83], v[50:51]
	v_pk_mul_f32 v[52:53], v[84:85], v[52:53]
	v_pk_mul_f32 v[54:55], v[86:87], v[54:55]
	v_pk_mul_f32 v[56:57], v[88:89], v[56:57]
	v_pk_mul_f32 v[58:59], v[90:91], v[58:59]
	v_pk_mul_f32 v[60:61], v[92:93], v[60:61]
	v_pk_mul_f32 v[62:63], v[94:95], v[62:63]
	global_store_dwordx4 v[24:25], v[32:35], off offset:-4096
	global_store_dwordx4 v[24:25], v[36:39], off offset:-3072
	global_store_dwordx4 v[24:25], v[40:43], off offset:-2048
	global_store_dwordx4 v[24:25], v[44:47], off offset:-1024
	global_store_dwordx4 v[24:25], v[48:51], off offset:0
	global_store_dwordx4 v[24:25], v[52:55], off offset:1024
	global_store_dwordx4 v[24:25], v[56:59], off offset:2048
	global_store_dwordx4 v[24:25], v[60:63], off offset:3072
	v_mov_b64_e32 v[24:25], v[12:13]
	s_waitcnt vmcnt(8)
	v_ffbh_u32_e32 v20, v129
	v_min_u32_e32 v20, 32, v20
	v_lshlrev_b64 v[128:129], v20, v[128:129]
	v_min_u32_e32 v128, 1, v128
	v_or_b32_e32 v128, v129, v128
	v_cvt_f32_u32_e32 v128, v128
	v_sub_u32_e32 v20, 32, v20
	v_ldexp_f32 v20, v128, v20
	v_fmamk_f32 v20, v20, 0x2e000000, v176
	v_mul_f32_e32 v128, 0x4b800000, v20
	v_cmp_gt_f32_e32 vcc, s7, v20
	s_nop 1
	v_cndmask_b32_e32 v20, v20, v128, vcc
	v_rsq_f32_e32 v20, v20
	s_nop 0
	v_mul_f32_e32 v128, 0x45800000, v20
	v_cndmask_b32_e32 v22, v20, v128, vcc
	v_pk_mul_f32 v[96:97], v[96:97], v[22:23] op_sel_hi:[1,0]
	v_pk_mul_f32 v[98:99], v[98:99], v[22:23] op_sel_hi:[1,0]
	v_pk_mul_f32 v[100:101], v[100:101], v[22:23] op_sel_hi:[1,0]
	v_pk_mul_f32 v[102:103], v[102:103], v[22:23] op_sel_hi:[1,0]
	v_pk_mul_f32 v[104:105], v[104:105], v[22:23] op_sel_hi:[1,0]
	v_pk_mul_f32 v[106:107], v[106:107], v[22:23] op_sel_hi:[1,0]
	v_pk_mul_f32 v[108:109], v[108:109], v[22:23] op_sel_hi:[1,0]
	v_pk_mul_f32 v[110:111], v[110:111], v[22:23] op_sel_hi:[1,0]
	v_pk_mul_f32 v[112:113], v[112:113], v[22:23] op_sel_hi:[1,0]
	v_pk_mul_f32 v[114:115], v[114:115], v[22:23] op_sel_hi:[1,0]
	v_pk_mul_f32 v[116:117], v[116:117], v[22:23] op_sel_hi:[1,0]
	v_pk_mul_f32 v[118:119], v[118:119], v[22:23] op_sel_hi:[1,0]
	v_pk_mul_f32 v[120:121], v[120:121], v[22:23] op_sel_hi:[1,0]
	v_pk_mul_f32 v[122:123], v[122:123], v[22:23] op_sel_hi:[1,0]
	v_pk_mul_f32 v[124:125], v[124:125], v[22:23] op_sel_hi:[1,0]
	v_pk_mul_f32 v[126:127], v[126:127], v[22:23] op_sel_hi:[1,0]
	v_pk_mul_f32 v[96:97], v[64:65], v[96:97]
	v_pk_mul_f32 v[98:99], v[66:67], v[98:99]
	v_pk_mul_f32 v[100:101], v[68:69], v[100:101]
	v_pk_mul_f32 v[102:103], v[70:71], v[102:103]
	v_pk_mul_f32 v[104:105], v[72:73], v[104:105]
	v_pk_mul_f32 v[106:107], v[74:75], v[106:107]
	v_pk_mul_f32 v[108:109], v[76:77], v[108:109]
	v_pk_mul_f32 v[110:111], v[78:79], v[110:111]
	v_pk_mul_f32 v[112:113], v[80:81], v[112:113]
	v_pk_mul_f32 v[114:115], v[82:83], v[114:115]
	v_pk_mul_f32 v[116:117], v[84:85], v[116:117]
	v_pk_mul_f32 v[118:119], v[86:87], v[118:119]
	v_pk_mul_f32 v[120:121], v[88:89], v[120:121]
	v_pk_mul_f32 v[122:123], v[90:91], v[122:123]
	v_pk_mul_f32 v[124:125], v[92:93], v[124:125]
	v_pk_mul_f32 v[126:127], v[94:95], v[126:127]
	global_store_dwordx4 v[24:25], v[96:99], off offset:-4096
	global_store_dwordx4 v[24:25], v[100:103], off offset:-3072
	global_store_dwordx4 v[24:25], v[104:107], off offset:-2048
	global_store_dwordx4 v[24:25], v[108:111], off offset:-1024
	global_store_dwordx4 v[24:25], v[112:115], off offset:0
	global_store_dwordx4 v[24:25], v[116:119], off offset:1024
	global_store_dwordx4 v[24:25], v[120:123], off offset:2048
	global_store_dwordx4 v[24:25], v[124:127], off offset:3072
	s_getpc_b64 s[98:99]
